# in-proj epilogue stores marked streaming (nt) in addition to write-through, to keep L2 for the GEMM operands
# speedup vs baseline: 1.0029x; 1.0029x over previous
.LBB0_293:
	s_ashr_i32 s67, s29, 11
	s_mul_i32 s12, s67, 0x50
	s_lshl_b32 s65, s44, 1
	s_add_i32 s38, s12, s65
	s_ashr_i32 s39, s38, 31
	s_lshl_b64 s[46:47], s[38:39], 19
	s_add_u32 s76, s30, s46
	v_lshlrev_b32_e32 v0, 8, v0
	s_addc_u32 s77, s31, s47
	s_waitcnt lgkmcnt(0)
	v_pk_mul_f32 v[136:137], v[136:137], v[164:165] op_sel_hi:[1,0]
	v_pk_mul_f32 v[134:135], v[134:135], v[164:165] op_sel_hi:[1,0]
	v_pk_mul_f32 v[132:133], v[132:133], v[164:165] op_sel_hi:[1,0]
	v_pk_mul_f32 v[166:167], v[130:131], v[164:165] op_sel_hi:[1,0]
	v_lshl_add_u64 v[130:131], s[76:77], 0, v[0:1]
	v_mov_b32_e32 v155, v1
	v_cndmask_b32_e64 v165, 0, 1, s[48:49]
	v_cmp_ne_u32_e64 s[46:47], 1, v165
	s_andn2_b64 vcc, exec, s[48:49]
	v_lshl_add_u64 v[168:169], v[130:131], 0, v[154:155]
	s_cbranch_vccnz .LBB0_295
	v_cvt_pk_bf16_f32 v190, v134, v135
	v_cvt_pk_bf16_f32 v191, v136, v137
	v_cvt_pk_bf16_f32 v192, v166, v167
	v_cvt_pk_bf16_f32 v193, v132, v133
	global_store_dwordx4 v[168:169], v[190:193], off sc1 nt

.LBB0_301:
	s_ashr_i32 s39, s28, 7
	s_add_i32 s4, s12, s39
	s_ashr_i32 s5, s4, 31
	s_lshl_b64 s[52:53], s[4:5], 19
	s_add_u32 s94, s30, s52
	v_cvt_pk_bf16_f32 v134, v134, v135
	v_cvt_pk_bf16_f32 v135, v136, v137
	v_cvt_pk_bf16_f32 v136, v166, v167
	v_cvt_pk_bf16_f32 v137, v132, v133
	v_mov_b32_e32 v132, v164
	v_mov_b32_e32 v133, v164
	s_addc_u32 s95, s31, s53
	v_mov_b32_e32 v165, v164
	global_store_dwordx4 v[170:171], v[134:137], off sc1 nt
	v_pk_mul_f32 v[128:129], v[128:129], v[132:133]
	v_pk_mul_f32 v[124:125], v[124:125], v[132:133]
	v_lshl_add_u64 v[132:133], s[94:95], 0, v[0:1]
	v_mov_b32_e32 v155, v1
	v_cndmask_b32_e64 v134, 0, 1, s[54:55]
	v_pk_mul_f32 v[126:127], v[126:127], v[164:165]
	v_pk_mul_f32 v[122:123], v[122:123], v[164:165]
	v_cmp_ne_u32_e64 s[52:53], 1, v134
	s_andn2_b64 vcc, exec, s[54:55]
	v_lshl_add_u64 v[132:133], v[132:133], 0, v[154:155]
	s_cbranch_vccnz .LBB0_303
	v_cvt_pk_bf16_f32 v134, v126, v127
	v_cvt_pk_bf16_f32 v135, v128, v129
	v_cvt_pk_bf16_f32 v136, v122, v123
	v_cvt_pk_bf16_f32 v137, v124, v125
	global_store_dwordx4 v[132:133], v[134:137], off sc1 nt

.LBB0_309:
	v_cvt_pk_bf16_f32 v126, v126, v127
	v_cvt_pk_bf16_f32 v127, v128, v129
	v_cvt_pk_bf16_f32 v128, v122, v123
	v_cvt_pk_bf16_f32 v129, v124, v125
	ds_read_b32 v122, v182 offset:64
	s_movk_i32 s5, 0x7df
	s_and_b64 vcc, exec, s[42:43]
	v_bitop3_b32 v0, v185, s5, 16 bitop3:0xc8
	global_store_dwordx4 v[134:135], v[126:129], off sc1 nt
	s_cbranch_vccnz .LBB0_311
	v_cvt_f32_u32_e32 v53, v0
	v_mul_f32_e32 v51, v178, v53
	v_mul_f32_e32 v52, v179, v53
	v_fract_f32_e32 v51, v51
	v_fract_f32_e32 v52, v52
	v_mul_f32_e32 v50, v174, v53
	v_cos_f32_e32 v156, v51
	v_sin_f32_e32 v54, v51
	v_mul_f32_e32 v51, v175, v53
	v_cos_f32_e32 v157, v52
	v_sin_f32_e32 v55, v52
	v_mul_f32_e32 v52, v176, v53
	v_mul_f32_e32 v56, v180, v53
	v_mul_f32_e32 v57, v177, v53
	v_mul_f32_e32 v123, v181, v53
	v_fract_f32_e32 v50, v50
	v_fract_f32_e32 v51, v51
	v_fract_f32_e32 v52, v52
	v_fract_f32_e32 v56, v56
	v_fract_f32_e32 v57, v57
	v_fract_f32_e32 v123, v123
	v_cos_f32_e32 v158, v50
	v_sin_f32_e32 v50, v50
	v_cos_f32_e32 v159, v51
	v_sin_f32_e32 v51, v51
	v_cos_f32_e32 v162, v52
	v_sin_f32_e32 v52, v52
	v_cos_f32_e32 v160, v56
	v_sin_f32_e32 v56, v56
	v_sin_f32_e32 v53, v57
	v_cos_f32_e32 v163, v57
	v_sin_f32_e32 v57, v123
	v_cos_f32_e32 v161, v123
	v_pk_mul_f32 v[52:53], v[148:149], v[52:53]
	v_pk_mul_f32 v[50:51], v[146:147], v[50:51]
	v_pk_mul_f32 v[56:57], v[148:149], v[56:57]
	v_pk_mul_f32 v[54:55], v[146:147], v[54:55]
.LBB0_311:
	v_lshlrev_b32_e32 v0, 8, v0
	s_waitcnt lgkmcnt(0)
	v_pk_mul_f32 v[124:125], v[114:115], v[122:123] op_sel_hi:[1,0]
	v_lshl_add_u64 v[114:115], s[76:77], 0, v[0:1]
	v_mov_b32_e32 v155, v1
	v_pk_mul_f32 v[120:121], v[120:121], v[122:123] op_sel_hi:[1,0]
	v_pk_mul_f32 v[118:119], v[118:119], v[122:123] op_sel_hi:[1,0]
	v_pk_mul_f32 v[116:117], v[116:117], v[122:123] op_sel_hi:[1,0]
	s_and_b64 vcc, exec, s[46:47]
	v_lshl_add_u64 v[126:127], v[114:115], 0, v[154:155]
	s_cbranch_vccnz .LBB0_313
	v_cvt_pk_bf16_f32 v128, v118, v119
	v_cvt_pk_bf16_f32 v129, v120, v121
	v_cvt_pk_bf16_f32 v130, v124, v125
	v_cvt_pk_bf16_f32 v131, v116, v117
	global_store_dwordx4 v[126:127], v[128:131], off sc1 nt

.LBB0_319:
	v_cvt_pk_bf16_f32 v118, v118, v119
	v_cvt_pk_bf16_f32 v119, v120, v121
	v_cvt_pk_bf16_f32 v120, v124, v125
	v_cvt_pk_bf16_f32 v121, v116, v117
	v_mov_b32_e32 v116, v122
	v_mov_b32_e32 v117, v122
	v_mov_b32_e32 v123, v122
	v_pk_mul_f32 v[112:113], v[112:113], v[116:117]
	v_pk_mul_f32 v[108:109], v[108:109], v[116:117]
	v_lshl_add_u64 v[116:117], s[94:95], 0, v[0:1]
	v_mov_b32_e32 v155, v1
	v_pk_mul_f32 v[110:111], v[110:111], v[122:123]
	v_pk_mul_f32 v[106:107], v[106:107], v[122:123]
	s_and_b64 vcc, exec, s[52:53]
	v_lshl_add_u64 v[116:117], v[116:117], 0, v[154:155]
	global_store_dwordx4 v[128:129], v[118:121], off sc1 nt
	s_cbranch_vccz .LBB0_418
	s_and_b64 vcc, exec, s[54:55]
	s_cbranch_vccz .LBB0_419

.LBB0_324:
	v_cvt_pk_bf16_f32 v110, v110, v111
	v_cvt_pk_bf16_f32 v111, v112, v113
	v_cvt_pk_bf16_f32 v112, v106, v107
	v_cvt_pk_bf16_f32 v113, v108, v109
	ds_read_b32 v106, v182 offset:128
	s_movk_i32 s5, 0x7ef
	s_and_b64 vcc, exec, s[42:43]
	v_bitop3_b32 v0, v185, s5, 32 bitop3:0xc8
	global_store_dwordx4 v[118:119], v[110:113], off sc1 nt
	s_cbranch_vccnz .LBB0_326
	v_cvt_f32_u32_e32 v53, v0
	v_mul_f32_e32 v51, v178, v53
	v_mul_f32_e32 v52, v179, v53
	v_fract_f32_e32 v51, v51
	v_fract_f32_e32 v52, v52
	v_mul_f32_e32 v50, v174, v53
	v_cos_f32_e32 v156, v51
	v_sin_f32_e32 v54, v51
	v_mul_f32_e32 v51, v175, v53
	v_cos_f32_e32 v157, v52
	v_sin_f32_e32 v55, v52
	v_mul_f32_e32 v52, v176, v53
	v_mul_f32_e32 v56, v180, v53
	v_mul_f32_e32 v57, v177, v53
	v_mul_f32_e32 v107, v181, v53
	v_fract_f32_e32 v50, v50
	v_fract_f32_e32 v51, v51
	v_fract_f32_e32 v52, v52
	v_fract_f32_e32 v56, v56
	v_fract_f32_e32 v57, v57
	v_fract_f32_e32 v107, v107
	v_cos_f32_e32 v158, v50
	v_sin_f32_e32 v50, v50
	v_cos_f32_e32 v159, v51
	v_sin_f32_e32 v51, v51
	v_cos_f32_e32 v162, v52
	v_sin_f32_e32 v52, v52
	v_cos_f32_e32 v160, v56
	v_sin_f32_e32 v56, v56
	v_sin_f32_e32 v53, v57
	v_cos_f32_e32 v163, v57
	v_sin_f32_e32 v57, v107
	v_cos_f32_e32 v161, v107
	v_pk_mul_f32 v[52:53], v[148:149], v[52:53]
	v_pk_mul_f32 v[50:51], v[146:147], v[50:51]
	v_pk_mul_f32 v[56:57], v[148:149], v[56:57]
	v_pk_mul_f32 v[54:55], v[146:147], v[54:55]
.LBB0_326:
	v_lshlrev_b32_e32 v0, 8, v0
	s_waitcnt lgkmcnt(0)
	v_pk_mul_f32 v[108:109], v[98:99], v[106:107] op_sel_hi:[1,0]
	v_lshl_add_u64 v[98:99], s[76:77], 0, v[0:1]
	v_mov_b32_e32 v155, v1
	v_pk_mul_f32 v[104:105], v[104:105], v[106:107] op_sel_hi:[1,0]
	v_pk_mul_f32 v[102:103], v[102:103], v[106:107] op_sel_hi:[1,0]
	v_pk_mul_f32 v[100:101], v[100:101], v[106:107] op_sel_hi:[1,0]
	s_and_b64 vcc, exec, s[46:47]
	v_lshl_add_u64 v[110:111], v[98:99], 0, v[154:155]
	s_cbranch_vccnz .LBB0_328
	v_cvt_pk_bf16_f32 v112, v102, v103
	v_cvt_pk_bf16_f32 v113, v104, v105
	v_cvt_pk_bf16_f32 v114, v108, v109
	v_cvt_pk_bf16_f32 v115, v100, v101
	global_store_dwordx4 v[110:111], v[112:115], off sc1 nt

.LBB0_334:
	v_cvt_pk_bf16_f32 v102, v102, v103
	v_cvt_pk_bf16_f32 v103, v104, v105
	v_cvt_pk_bf16_f32 v104, v108, v109
	v_cvt_pk_bf16_f32 v105, v100, v101
	v_mov_b32_e32 v100, v106
	v_mov_b32_e32 v101, v106
	v_mov_b32_e32 v107, v106
	v_pk_mul_f32 v[96:97], v[96:97], v[100:101]
	v_pk_mul_f32 v[92:93], v[92:93], v[100:101]
	v_lshl_add_u64 v[100:101], s[94:95], 0, v[0:1]
	v_mov_b32_e32 v155, v1
	v_pk_mul_f32 v[94:95], v[94:95], v[106:107]
	v_pk_mul_f32 v[90:91], v[90:91], v[106:107]
	s_and_b64 vcc, exec, s[52:53]
	v_lshl_add_u64 v[100:101], v[100:101], 0, v[154:155]
	global_store_dwordx4 v[112:113], v[102:105], off sc1 nt
	s_cbranch_vccz .LBB0_421
	s_and_b64 vcc, exec, s[54:55]
	s_cbranch_vccz .LBB0_422

.LBB0_339:
	v_cvt_pk_bf16_f32 v94, v94, v95
	v_cvt_pk_bf16_f32 v95, v96, v97
	v_cvt_pk_bf16_f32 v96, v90, v91
	v_cvt_pk_bf16_f32 v97, v92, v93
	ds_read_b32 v90, v182 offset:192
	s_and_b64 vcc, exec, s[42:43]
	v_bitop3_b32 v0, v185, s91, 48 bitop3:0xc8
	global_store_dwordx4 v[102:103], v[94:97], off sc1 nt
	s_cbranch_vccnz .LBB0_341
	v_cvt_f32_u32_e32 v53, v0
	v_mul_f32_e32 v51, v178, v53
	v_mul_f32_e32 v52, v179, v53
	v_fract_f32_e32 v51, v51
	v_fract_f32_e32 v52, v52
	v_mul_f32_e32 v50, v174, v53
	v_cos_f32_e32 v156, v51
	v_sin_f32_e32 v54, v51
	v_mul_f32_e32 v51, v175, v53
	v_cos_f32_e32 v157, v52
	v_sin_f32_e32 v55, v52
	v_mul_f32_e32 v52, v176, v53
	v_mul_f32_e32 v56, v180, v53
	v_mul_f32_e32 v57, v177, v53
	v_mul_f32_e32 v91, v181, v53
	v_fract_f32_e32 v50, v50
	v_fract_f32_e32 v51, v51
	v_fract_f32_e32 v52, v52
	v_fract_f32_e32 v56, v56
	v_fract_f32_e32 v57, v57
	v_fract_f32_e32 v91, v91
	v_cos_f32_e32 v158, v50
	v_sin_f32_e32 v50, v50
	v_cos_f32_e32 v159, v51
	v_sin_f32_e32 v51, v51
	v_cos_f32_e32 v162, v52
	v_sin_f32_e32 v52, v52
	v_cos_f32_e32 v160, v56
	v_sin_f32_e32 v56, v56
	v_sin_f32_e32 v53, v57
	v_cos_f32_e32 v163, v57
	v_sin_f32_e32 v57, v91
	v_cos_f32_e32 v161, v91
	v_pk_mul_f32 v[52:53], v[148:149], v[52:53]
	v_pk_mul_f32 v[50:51], v[146:147], v[50:51]
	v_pk_mul_f32 v[56:57], v[148:149], v[56:57]
	v_pk_mul_f32 v[54:55], v[146:147], v[54:55]
.LBB0_341:
	v_lshlrev_b32_e32 v0, 8, v0
	s_waitcnt lgkmcnt(0)
	v_pk_mul_f32 v[92:93], v[82:83], v[90:91] op_sel_hi:[1,0]
	v_lshl_add_u64 v[82:83], s[76:77], 0, v[0:1]
	v_mov_b32_e32 v155, v1
	v_pk_mul_f32 v[88:89], v[88:89], v[90:91] op_sel_hi:[1,0]
	v_pk_mul_f32 v[86:87], v[86:87], v[90:91] op_sel_hi:[1,0]
	v_pk_mul_f32 v[84:85], v[84:85], v[90:91] op_sel_hi:[1,0]
	s_and_b64 vcc, exec, s[46:47]
	v_lshl_add_u64 v[94:95], v[82:83], 0, v[154:155]
	s_cbranch_vccnz .LBB0_343
	v_cvt_pk_bf16_f32 v96, v86, v87
	v_cvt_pk_bf16_f32 v97, v88, v89
	v_cvt_pk_bf16_f32 v98, v92, v93
	v_cvt_pk_bf16_f32 v99, v84, v85
	global_store_dwordx4 v[94:95], v[96:99], off sc1 nt

.LBB0_349:
	v_cvt_pk_bf16_f32 v86, v86, v87
	v_cvt_pk_bf16_f32 v87, v88, v89
	v_cvt_pk_bf16_f32 v88, v92, v93
	v_cvt_pk_bf16_f32 v89, v84, v85
	v_mov_b32_e32 v84, v90
	v_mov_b32_e32 v85, v90
	v_mov_b32_e32 v91, v90
	v_pk_mul_f32 v[80:81], v[80:81], v[84:85]
	v_pk_mul_f32 v[76:77], v[76:77], v[84:85]
	v_lshl_add_u64 v[84:85], s[94:95], 0, v[0:1]
	v_mov_b32_e32 v155, v1
	v_pk_mul_f32 v[78:79], v[78:79], v[90:91]
	v_pk_mul_f32 v[74:75], v[74:75], v[90:91]
	s_and_b64 vcc, exec, s[52:53]
	v_lshl_add_u64 v[84:85], v[84:85], 0, v[154:155]
	global_store_dwordx4 v[96:97], v[86:89], off sc1 nt
	s_cbranch_vccz .LBB0_424
	s_and_b64 vcc, exec, s[54:55]
	s_cbranch_vccz .LBB0_425

.LBB0_354:
	v_cvt_pk_bf16_f32 v78, v78, v79
	v_cvt_pk_bf16_f32 v79, v80, v81
	v_cvt_pk_bf16_f32 v80, v74, v75
	v_cvt_pk_bf16_f32 v81, v76, v77
	ds_read_b32 v74, v182 offset:512
	global_store_dwordx4 v[86:87], v[78:81], off sc1 nt
	v_add_u32_e32 v86, 0x80, v185
	s_and_b64 vcc, exec, s[42:43]
	v_and_b32_e32 v0, 0x7cf, v86
	s_cbranch_vccnz .LBB0_356
	v_cvt_f32_u32_e32 v53, v0
	v_mul_f32_e32 v51, v178, v53
	v_mul_f32_e32 v52, v179, v53
	v_fract_f32_e32 v51, v51
	v_fract_f32_e32 v52, v52
	v_mul_f32_e32 v50, v174, v53
	v_cos_f32_e32 v156, v51
	v_sin_f32_e32 v54, v51
	v_mul_f32_e32 v51, v175, v53
	v_cos_f32_e32 v157, v52
	v_sin_f32_e32 v55, v52
	v_mul_f32_e32 v52, v176, v53
	v_mul_f32_e32 v56, v180, v53
	v_mul_f32_e32 v57, v177, v53
	v_mul_f32_e32 v75, v181, v53
	v_fract_f32_e32 v50, v50
	v_fract_f32_e32 v51, v51
	v_fract_f32_e32 v52, v52
	v_fract_f32_e32 v56, v56
	v_fract_f32_e32 v57, v57
	v_fract_f32_e32 v75, v75
	v_cos_f32_e32 v158, v50
	v_sin_f32_e32 v50, v50
	v_cos_f32_e32 v159, v51
	v_sin_f32_e32 v51, v51
	v_cos_f32_e32 v162, v52
	v_sin_f32_e32 v52, v52
	v_cos_f32_e32 v160, v56
	v_sin_f32_e32 v56, v56
	v_sin_f32_e32 v53, v57
	v_cos_f32_e32 v163, v57
	v_sin_f32_e32 v57, v75
	v_cos_f32_e32 v161, v75
	v_pk_mul_f32 v[52:53], v[148:149], v[52:53]
	v_pk_mul_f32 v[50:51], v[146:147], v[50:51]
	v_pk_mul_f32 v[56:57], v[148:149], v[56:57]
	v_pk_mul_f32 v[54:55], v[146:147], v[54:55]
.LBB0_356:
	v_ashrrev_i32_e32 v87, 11, v86
	s_waitcnt lgkmcnt(0)
	v_pk_mul_f32 v[80:81], v[66:67], v[74:75] op_sel_hi:[1,0]
	v_mov_b32_e32 v66, s65
	s_movk_i32 s4, 0x50
	v_pk_mul_f32 v[76:77], v[68:69], v[74:75] op_sel_hi:[1,0]
	v_mad_i32_i24 v68, v87, s4, v66
	v_ashrrev_i32_e32 v69, 31, v68
	v_lshlrev_b64 v[66:67], 19, v[68:69]
	v_lshlrev_b32_e32 v0, 8, v0
	v_lshl_add_u64 v[66:67], s[30:31], 0, v[66:67]
	v_pk_mul_f32 v[78:79], v[70:71], v[74:75] op_sel_hi:[1,0]
	v_lshl_add_u64 v[70:71], v[66:67], 0, v[0:1]
	v_mov_b32_e32 v155, v1
	v_pk_mul_f32 v[72:73], v[72:73], v[74:75] op_sel_hi:[1,0]
	s_and_b64 vcc, exec, s[46:47]
	v_lshl_add_u64 v[82:83], v[70:71], 0, v[154:155]
	s_cbranch_vccnz .LBB0_358
	v_cvt_pk_bf16_f32 v88, v78, v79
	v_cvt_pk_bf16_f32 v89, v72, v73
	v_cvt_pk_bf16_f32 v90, v80, v81
	v_cvt_pk_bf16_f32 v91, v76, v77
	global_store_dwordx4 v[82:83], v[88:91], off sc1 nt

.LBB0_364:
	v_mul_i32_i24_e32 v82, 0x50, v87
	v_mov_b32_e32 v75, v74
	v_cvt_pk_bf16_f32 v78, v78, v79
	v_cvt_pk_bf16_f32 v79, v72, v73
	v_cvt_pk_bf16_f32 v80, v80, v81
	v_cvt_pk_bf16_f32 v81, v76, v77
	v_mov_b32_e32 v76, v74
	v_mov_b32_e32 v77, v74
	v_pk_mul_f32 v[72:73], v[62:63], v[74:75]
	v_pk_mul_f32 v[62:63], v[60:61], v[76:77]
	v_add_u32_e32 v60, s39, v82
	v_ashrrev_i32_e32 v61, 31, v60
	v_pk_mul_f32 v[74:75], v[58:59], v[74:75]
	v_lshlrev_b64 v[58:59], 19, v[60:61]
	v_lshl_add_u64 v[58:59], s[30:31], 0, v[58:59]
	v_pk_mul_f32 v[64:65], v[64:65], v[76:77]
	v_lshl_add_u64 v[76:77], v[58:59], 0, v[0:1]
	v_mov_b32_e32 v155, v1
	s_and_b64 vcc, exec, s[52:53]
	v_lshl_add_u64 v[76:77], v[76:77], 0, v[154:155]
	global_store_dwordx4 v[84:85], v[78:81], off sc1 nt
	s_cbranch_vccz .LBB0_427
	s_and_b64 vcc, exec, s[54:55]
	s_cbranch_vccz .LBB0_428

.LBB0_370:
	v_cvt_pk_bf16_f32 v70, v72, v73
	v_cvt_pk_bf16_f32 v71, v64, v65
	v_cvt_pk_bf16_f32 v72, v74, v75
	v_cvt_pk_bf16_f32 v73, v62, v63
	ds_read_b32 v62, v182 offset:576
	s_movk_i32 s4, 0x7df
	s_and_b64 vcc, exec, s[42:43]
	v_bitop3_b32 v0, v86, s4, 16 bitop3:0xc8
	global_store_dwordx4 v[78:79], v[70:73], off sc1 nt
	s_cbranch_vccnz .LBB0_372
	v_cvt_f32_u32_e32 v53, v0
	v_mul_f32_e32 v51, v178, v53
	v_mul_f32_e32 v52, v179, v53
	v_fract_f32_e32 v51, v51
	v_fract_f32_e32 v52, v52
	v_mul_f32_e32 v50, v174, v53
	v_cos_f32_e32 v156, v51
	v_sin_f32_e32 v54, v51
	v_mul_f32_e32 v51, v175, v53
	v_cos_f32_e32 v157, v52
	v_sin_f32_e32 v55, v52
	v_mul_f32_e32 v52, v176, v53
	v_mul_f32_e32 v56, v180, v53
	v_mul_f32_e32 v57, v177, v53
	v_mul_f32_e32 v63, v181, v53
	v_fract_f32_e32 v50, v50
	v_fract_f32_e32 v51, v51
	v_fract_f32_e32 v52, v52
	v_fract_f32_e32 v56, v56
	v_fract_f32_e32 v57, v57
	v_fract_f32_e32 v63, v63
	v_cos_f32_e32 v158, v50
	v_sin_f32_e32 v50, v50
	v_cos_f32_e32 v159, v51
	v_sin_f32_e32 v51, v51
	v_cos_f32_e32 v162, v52
	v_sin_f32_e32 v52, v52
	v_cos_f32_e32 v160, v56
	v_sin_f32_e32 v56, v56
	v_sin_f32_e32 v53, v57
	v_cos_f32_e32 v163, v57
	v_sin_f32_e32 v57, v63
	v_cos_f32_e32 v161, v63
	v_pk_mul_f32 v[52:53], v[148:149], v[52:53]
	v_pk_mul_f32 v[50:51], v[146:147], v[50:51]
	v_pk_mul_f32 v[56:57], v[148:149], v[56:57]
	v_pk_mul_f32 v[54:55], v[146:147], v[54:55]
.LBB0_372:
	v_lshlrev_b32_e32 v0, 8, v0
	s_waitcnt lgkmcnt(0)
	v_pk_mul_f32 v[64:65], v[42:43], v[62:63] op_sel_hi:[1,0]
	v_lshl_add_u64 v[42:43], v[66:67], 0, v[0:1]
	v_mov_b32_e32 v155, v1
	v_pk_mul_f32 v[48:49], v[48:49], v[62:63] op_sel_hi:[1,0]
	v_pk_mul_f32 v[46:47], v[46:47], v[62:63] op_sel_hi:[1,0]
	v_pk_mul_f32 v[44:45], v[44:45], v[62:63] op_sel_hi:[1,0]
	s_and_b64 vcc, exec, s[46:47]
	v_lshl_add_u64 v[70:71], v[42:43], 0, v[154:155]
	s_cbranch_vccnz .LBB0_374
	v_cvt_pk_bf16_f32 v72, v46, v47
	v_cvt_pk_bf16_f32 v73, v48, v49
	v_cvt_pk_bf16_f32 v74, v64, v65
	v_cvt_pk_bf16_f32 v75, v44, v45
	global_store_dwordx4 v[70:71], v[72:75], off sc1 nt

.LBB0_380:
	v_cvt_pk_bf16_f32 v46, v46, v47
	v_cvt_pk_bf16_f32 v47, v48, v49
	v_cvt_pk_bf16_f32 v48, v64, v65
	v_cvt_pk_bf16_f32 v49, v44, v45
	v_mov_b32_e32 v44, v62
	v_mov_b32_e32 v45, v62
	v_mov_b32_e32 v63, v62
	v_pk_mul_f32 v[40:41], v[40:41], v[44:45]
	v_pk_mul_f32 v[36:37], v[36:37], v[44:45]
	v_lshl_add_u64 v[44:45], v[58:59], 0, v[0:1]
	v_mov_b32_e32 v155, v1
	v_pk_mul_f32 v[38:39], v[38:39], v[62:63]
	v_pk_mul_f32 v[34:35], v[34:35], v[62:63]
	s_and_b64 vcc, exec, s[52:53]
	v_lshl_add_u64 v[44:45], v[44:45], 0, v[154:155]
	global_store_dwordx4 v[72:73], v[46:49], off sc1 nt
	s_cbranch_vccz .LBB0_429
	s_and_b64 vcc, exec, s[54:55]
	s_cbranch_vccz .LBB0_430

.LBB0_385:
	v_cvt_pk_bf16_f32 v38, v38, v39
	v_cvt_pk_bf16_f32 v39, v40, v41
	v_cvt_pk_bf16_f32 v40, v34, v35
	v_cvt_pk_bf16_f32 v41, v36, v37
	ds_read_b32 v34, v182 offset:640
	s_movk_i32 s4, 0x7ef
	s_and_b64 vcc, exec, s[42:43]
	v_bitop3_b32 v0, v86, s4, 32 bitop3:0xc8
	global_store_dwordx4 v[46:47], v[38:41], off sc1 nt
	s_cbranch_vccnz .LBB0_387
	v_cvt_f32_u32_e32 v35, v0
	v_mul_f32_e32 v37, v178, v35
	v_mul_f32_e32 v41, v180, v35
	v_fract_f32_e32 v37, v37
	v_fract_f32_e32 v41, v41
	v_mul_f32_e32 v36, v174, v35
	v_cos_f32_e32 v156, v37
	v_sin_f32_e32 v38, v37
	v_mul_f32_e32 v37, v175, v35
	v_mul_f32_e32 v39, v179, v35
	v_mul_f32_e32 v40, v176, v35
	v_cos_f32_e32 v160, v41
	v_sin_f32_e32 v42, v41
	v_mul_f32_e32 v41, v177, v35
	v_mul_f32_e32 v35, v181, v35
	v_fract_f32_e32 v36, v36
	v_fract_f32_e32 v37, v37
	v_fract_f32_e32 v39, v39
	v_fract_f32_e32 v40, v40
	v_fract_f32_e32 v43, v41
	v_fract_f32_e32 v35, v35
	v_cos_f32_e32 v158, v36
	v_sin_f32_e32 v36, v36
	v_cos_f32_e32 v159, v37
	v_sin_f32_e32 v37, v37
	v_cos_f32_e32 v157, v39
	v_sin_f32_e32 v39, v39
	v_cos_f32_e32 v162, v40
	v_sin_f32_e32 v40, v40
	v_sin_f32_e32 v41, v43
	v_cos_f32_e32 v163, v43
	v_sin_f32_e32 v43, v35
	v_cos_f32_e32 v161, v35
	v_pk_mul_f32 v[52:53], v[148:149], v[40:41]
	v_pk_mul_f32 v[50:51], v[146:147], v[36:37]
	v_pk_mul_f32 v[56:57], v[148:149], v[42:43]
	v_pk_mul_f32 v[54:55], v[146:147], v[38:39]
.LBB0_387:
	v_lshlrev_b32_e32 v0, 8, v0
	s_waitcnt lgkmcnt(0)
	v_pk_mul_f32 v[36:37], v[26:27], v[34:35] op_sel_hi:[1,0]
	v_lshl_add_u64 v[26:27], v[66:67], 0, v[0:1]
	v_mov_b32_e32 v155, v1
	v_pk_mul_f32 v[32:33], v[32:33], v[34:35] op_sel_hi:[1,0]
	v_pk_mul_f32 v[30:31], v[30:31], v[34:35] op_sel_hi:[1,0]
	v_pk_mul_f32 v[28:29], v[28:29], v[34:35] op_sel_hi:[1,0]
	s_and_b64 vcc, exec, s[46:47]
	v_lshl_add_u64 v[38:39], v[26:27], 0, v[154:155]
	s_cbranch_vccnz .LBB0_389
	v_cvt_pk_bf16_f32 v40, v30, v31
	v_cvt_pk_bf16_f32 v41, v32, v33
	v_cvt_pk_bf16_f32 v42, v36, v37
	v_cvt_pk_bf16_f32 v43, v28, v29
	global_store_dwordx4 v[38:39], v[40:43], off sc1 nt

.LBB0_395:
	v_cvt_pk_bf16_f32 v30, v30, v31
	v_cvt_pk_bf16_f32 v31, v32, v33
	v_cvt_pk_bf16_f32 v32, v36, v37
	v_cvt_pk_bf16_f32 v33, v28, v29
	v_mov_b32_e32 v28, v34
	v_mov_b32_e32 v29, v34
	v_mov_b32_e32 v35, v34
	v_pk_mul_f32 v[24:25], v[24:25], v[28:29]
	v_pk_mul_f32 v[20:21], v[20:21], v[28:29]
	v_lshl_add_u64 v[28:29], v[58:59], 0, v[0:1]
	v_mov_b32_e32 v155, v1
	v_pk_mul_f32 v[22:23], v[22:23], v[34:35]
	v_pk_mul_f32 v[18:19], v[18:19], v[34:35]
	s_and_b64 vcc, exec, s[52:53]
	v_lshl_add_u64 v[28:29], v[28:29], 0, v[154:155]
	global_store_dwordx4 v[40:41], v[30:33], off sc1 nt
	s_cbranch_vccz .LBB0_432
	s_and_b64 vcc, exec, s[54:55]
	s_cbranch_vccz .LBB0_433

.LBB0_400:
	v_cvt_pk_bf16_f32 v22, v22, v23
	v_cvt_pk_bf16_f32 v23, v24, v25
	v_cvt_pk_bf16_f32 v24, v18, v19
	v_cvt_pk_bf16_f32 v25, v20, v21
	ds_read_b32 v18, v182 offset:704
	s_and_b64 vcc, exec, s[42:43]
	v_bitop3_b32 v0, v86, s91, 48 bitop3:0xc8
	global_store_dwordx4 v[30:31], v[22:25], off sc1 nt
	s_cbranch_vccnz .LBB0_402
	v_cvt_f32_u32_e32 v19, v0
	v_mul_f32_e32 v21, v178, v19
	v_mul_f32_e32 v25, v180, v19
	v_fract_f32_e32 v21, v21
	v_fract_f32_e32 v25, v25
	v_mul_f32_e32 v20, v174, v19
	v_cos_f32_e32 v156, v21
	v_sin_f32_e32 v22, v21
	v_mul_f32_e32 v21, v175, v19
	v_mul_f32_e32 v23, v179, v19
	v_mul_f32_e32 v24, v176, v19
	v_cos_f32_e32 v160, v25
	v_sin_f32_e32 v26, v25
	v_mul_f32_e32 v25, v177, v19
	v_mul_f32_e32 v19, v181, v19
	v_fract_f32_e32 v20, v20
	v_fract_f32_e32 v21, v21
	v_fract_f32_e32 v23, v23
	v_fract_f32_e32 v24, v24
	v_fract_f32_e32 v27, v25
	v_fract_f32_e32 v19, v19
	v_cos_f32_e32 v158, v20
	v_sin_f32_e32 v20, v20
	v_cos_f32_e32 v159, v21
	v_sin_f32_e32 v21, v21
	v_cos_f32_e32 v157, v23
	v_sin_f32_e32 v23, v23
	v_cos_f32_e32 v162, v24
	v_sin_f32_e32 v24, v24
	v_sin_f32_e32 v25, v27
	v_cos_f32_e32 v163, v27
	v_sin_f32_e32 v27, v19
	v_cos_f32_e32 v161, v19
	v_pk_mul_f32 v[52:53], v[148:149], v[24:25]
	v_pk_mul_f32 v[50:51], v[146:147], v[20:21]
	v_pk_mul_f32 v[56:57], v[148:149], v[26:27]
	v_pk_mul_f32 v[54:55], v[146:147], v[22:23]
.LBB0_402:
	v_lshlrev_b32_e32 v0, 8, v0
	s_waitcnt lgkmcnt(0)
	v_pk_mul_f32 v[20:21], v[10:11], v[18:19] op_sel_hi:[1,0]
	v_lshl_add_u64 v[10:11], v[66:67], 0, v[0:1]
	v_mov_b32_e32 v155, v1
	v_pk_mul_f32 v[16:17], v[16:17], v[18:19] op_sel_hi:[1,0]
	v_pk_mul_f32 v[14:15], v[14:15], v[18:19] op_sel_hi:[1,0]
	v_pk_mul_f32 v[12:13], v[12:13], v[18:19] op_sel_hi:[1,0]
	s_and_b64 vcc, exec, s[46:47]
	v_lshl_add_u64 v[22:23], v[10:11], 0, v[154:155]
	s_cbranch_vccnz .LBB0_404
	v_cvt_pk_bf16_f32 v24, v14, v15
	v_cvt_pk_bf16_f32 v25, v16, v17
	v_cvt_pk_bf16_f32 v26, v20, v21
	v_cvt_pk_bf16_f32 v27, v12, v13
	global_store_dwordx4 v[22:23], v[24:27], off sc1 nt

.LBB0_410:
	v_cvt_pk_bf16_f32 v14, v14, v15
	v_cvt_pk_bf16_f32 v15, v16, v17
	v_cvt_pk_bf16_f32 v16, v20, v21
	v_cvt_pk_bf16_f32 v17, v12, v13
	v_mov_b32_e32 v12, v18
	v_mov_b32_e32 v13, v18
	v_mov_b32_e32 v19, v18
	v_pk_mul_f32 v[8:9], v[8:9], v[12:13]
	v_pk_mul_f32 v[4:5], v[4:5], v[12:13]
	v_lshl_add_u64 v[12:13], v[58:59], 0, v[0:1]
	v_mov_b32_e32 v155, v1
	v_pk_mul_f32 v[6:7], v[6:7], v[18:19]
	v_pk_mul_f32 v[2:3], v[2:3], v[18:19]
	s_and_b64 vcc, exec, s[52:53]
	v_lshl_add_u64 v[12:13], v[12:13], 0, v[154:155]
	global_store_dwordx4 v[24:25], v[14:17], off sc1 nt
	s_cbranch_vccz .LBB0_435
	s_and_b64 vcc, exec, s[54:55]
	s_cbranch_vccz .LBB0_436

.LBB0_415:
	s_andn2_b64 vcc, exec, s[40:41]
	s_mov_b64 s[4:5], -1
	v_cvt_pk_bf16_f32 v6, v6, v7
	v_cvt_pk_bf16_f32 v7, v8, v9
	v_cvt_pk_bf16_f32 v8, v2, v3
	v_cvt_pk_bf16_f32 v9, v4, v5
	global_store_dwordx4 v[14:15], v[6:9], off sc1 nt
	s_cbranch_vccnz .LBB0_280
	s_andn2_b64 vcc, exec, s[18:19]
	s_cbranch_vccnz .LBB0_279
	s_barrier
	s_branch .LBB0_279
.LBB0_418:
	s_nop 0
	v_cvt_pk_bf16_f32 v118, v110, v111
	v_cvt_pk_bf16_f32 v119, v112, v113
	v_cvt_pk_bf16_f32 v120, v106, v107
	v_cvt_pk_bf16_f32 v121, v108, v109
	global_store_dwordx4 v[116:117], v[118:121], off sc1 nt
	s_and_b64 vcc, exec, s[54:55]
	s_cbranch_vccnz .LBB0_321

.LBB0_421:
	s_nop 0
	v_cvt_pk_bf16_f32 v102, v94, v95
	v_cvt_pk_bf16_f32 v103, v96, v97
	v_cvt_pk_bf16_f32 v104, v90, v91
	v_cvt_pk_bf16_f32 v105, v92, v93
	global_store_dwordx4 v[100:101], v[102:105], off sc1 nt
	s_and_b64 vcc, exec, s[54:55]
	s_cbranch_vccnz .LBB0_336

.LBB0_424:
	s_nop 0
	v_cvt_pk_bf16_f32 v86, v78, v79
	v_cvt_pk_bf16_f32 v87, v80, v81
	v_cvt_pk_bf16_f32 v88, v74, v75
	v_cvt_pk_bf16_f32 v89, v76, v77
	global_store_dwordx4 v[84:85], v[86:89], off sc1 nt
	s_and_b64 vcc, exec, s[54:55]
	s_cbranch_vccnz .LBB0_351

.LBB0_427:
	s_nop 0
	v_cvt_pk_bf16_f32 v78, v72, v73
	v_cvt_pk_bf16_f32 v79, v64, v65
	v_cvt_pk_bf16_f32 v80, v74, v75
	v_cvt_pk_bf16_f32 v81, v62, v63
	global_store_dwordx4 v[76:77], v[78:81], off sc1 nt
	s_and_b64 vcc, exec, s[54:55]
	s_cbranch_vccnz .LBB0_366

.LBB0_429:
	s_nop 0
	v_cvt_pk_bf16_f32 v46, v38, v39
	v_cvt_pk_bf16_f32 v47, v40, v41
	v_cvt_pk_bf16_f32 v48, v34, v35
	v_cvt_pk_bf16_f32 v49, v36, v37
	global_store_dwordx4 v[44:45], v[46:49], off sc1 nt
	s_and_b64 vcc, exec, s[54:55]
	s_cbranch_vccnz .LBB0_382

.LBB0_432:
	s_nop 0
	v_cvt_pk_bf16_f32 v30, v22, v23
	v_cvt_pk_bf16_f32 v31, v24, v25
	v_cvt_pk_bf16_f32 v32, v18, v19
	v_cvt_pk_bf16_f32 v33, v20, v21
	global_store_dwordx4 v[28:29], v[30:33], off sc1 nt
	s_and_b64 vcc, exec, s[54:55]
	s_cbranch_vccnz .LBB0_397

.LBB0_435:
	s_nop 0
	v_cvt_pk_bf16_f32 v14, v6, v7
	v_cvt_pk_bf16_f32 v15, v8, v9
	v_cvt_pk_bf16_f32 v16, v2, v3
	v_cvt_pk_bf16_f32 v17, v4, v5
	global_store_dwordx4 v[12:13], v[14:17], off sc1 nt
	s_and_b64 vcc, exec, s[54:55]
	s_cbranch_vccnz .LBB0_412
